# short-conv loop double-buffered: next row's 4 loads issued before computing the current row, scalar-base addressing, counted vmcnt(4)
# baseline (speedup 1.0000x reference)
; __device__ __forceinline__ u32x4 pack8(f32x4 a, f32x4 b) { u32x4 w; w.x = pk2(a[0], a[1]); w.y = pk2(a[2], a[3]); w.z = pk2(b[0], b[1]); w.w = pk2(b[2], b[3]); return w; }
; __device__ __forceinline__ void unpack8(u32x4 w, f32x4& a, f32x4& b) { a = (f32x4){bflo(w.x), bfhi(w.x), bflo(w.y), bfhi(w.y)}; b = (f32x4){bflo(w.z), bfhi(w.z), bflo(w.w), bfhi(w.w)}; }
; __global__ void __launch_bounds__(512, 2) mk_fwd(Args a) {
;     ...
;             const float* cw = ap->in[12] + (size_t)layer * 1536; float w0[8], w1[8], w2[8];
; #pragma unroll
;             for (int e = 0; e < 8; ++e) { w0[e] = cw[8 * lane + e]; w1[e] = cw[512 + 8 * lane + e]; w2[e] = cw[1024 + 8 * lane + e]; }
;             for (int row = gw; row < T; row += NGW) {
;                 const int pos = tok_pos(row), S_ = row < TP ? 4096 : 8192;
;                 const u32x4 zc = *(const u32x4*)(CONVZ + (size_t)row * 512 + 8 * lane), bb = *(const u32x4*)(CONVB + (size_t)row * 512 + 8 * lane);
;                 u32x4 zp = (u32x4){0u, 0u, 0u, 0u}, zn = zp;
;                 if (pos > 0) zp = *(const u32x4*)(CONVZ + (size_t)(row - 1) * 512 + 8 * lane);
;                 if (pos < S_ - 1) zn = *(const u32x4*)(CONVZ + (size_t)(row + 1) * 512 + 8 * lane);
;                 f32x4 c0, c1, p0, p1, n0, n1, b0, b1; unpack8(zc, c0, c1); unpack8(zp, p0, p1); unpack8(zn, n0, n1); unpack8(bb, b0, b1);
;                 f32x4 y0, y1;
; #pragma unroll
;                 for (int e = 0; e < 4; ++e) { y0[e] = b0[e] * (w0[e] * p0[e] + w1[e] * c0[e] + w2[e] * n0[e]); y1[e] = b1[e] * (w0[4 + e] * p1[e] + w1[4 + e] * c1[e] + w2[4 + e] * n1[e]); }
;                 *(u32x4*)(CB + (size_t)row * 512 + 8 * lane) = pack8(y0, y1);
;             }
.LBB0_1545:
	s_and_b64 vcc, exec, s[16:17]
	s_cbranch_vccz .LBB0_1554
	v_readlane_b32 s8, v253, 63
	v_mov_b32_e32 v26, v230
	s_cmpk_gt_i32 s2, 0x7fff
	v_readlane_b32 s9, v254, 0
	s_cbranch_scc1 .LBB0_1558
	v_readlane_b32 s4, v254, 40
	v_readlane_b32 s5, v254, 41
	s_load_dwordx2 s[4:5], s[4:5], 0x60
	v_readlane_b32 s6, v254, 46
	s_mul_hi_i32 s3, s6, 0x1800
	s_mulk_i32 s6, 0x1800
	v_lshlrev_b32_e32 v0, 3, v26
	v_and_b32_e32 v27, 0x1f8, v0
	s_waitcnt lgkmcnt(0)
	s_add_u32 s4, s4, s6
	v_readlane_b32 s7, v254, 47
	s_addc_u32 s5, s5, s3
	v_lshlrev_b32_e32 v0, 2, v27
	v_lshl_add_u64 v[18:19], s[4:5], 0, v[0:1]
	s_mov_b64 s[6:7], 0x1000
	s_movk_i32 s3, 0x1000
	v_lshl_add_u64 v[22:23], v[18:19], 0, s[6:7]
	global_load_dwordx4 v[2:5], v0, s[4:5] offset:16
	global_load_dwordx4 v[6:9], v0, s[4:5]
	global_load_dwordx4 v[10:13], v0, s[4:5] offset:2064
	global_load_dwordx4 v[14:17], v0, s[4:5] offset:2048
	v_add_co_u32_e32 v18, vcc, s3, v18
	v_readlane_b32 s4, v255, 2
	s_nop 0
	v_addc_co_u32_e32 v19, vcc, 0, v19, vcc
	global_load_dwordx4 v[18:21], v[18:19], off
	s_nop 0
	global_load_dwordx4 v[22:25], v[22:23], off offset:16
	v_lshlrev_b32_e32 v0, 1, v27
	v_readlane_b32 s5, v255, 3
	s_ashr_i32 s3, s2, 31
	s_nop 0
	v_lshl_add_u64 v[42:43], s[4:5], 0, v[0:1]
	s_lshl_b64 s[4:5], s[2:3], 10
	v_and_b32_e32 v0, 63, v26
	s_add_u32 s4, s38, s4
	v_lshlrev_b32_e32 v0, 4, v0
	s_addc_u32 s5, s39, s5
	v_lshl_add_u64 v[26:27], s[4:5], 0, v[0:1]
	s_mov_b64 s[4:5], 0x11000000
	v_lshl_add_u64 v[44:45], v[26:27], 0, s[4:5]
	s_mov_b32 s3, s2
	v_readlane_b32 s98, v255, 2
	v_readlane_b32 s99, v255, 3
	s_nop 3
	s_nop 0
	s_lshl_b32 s6, s3, 10
	s_add_u32 s4, s98, s6
	s_addc_u32 s5, s99, 0
	global_load_dwordx4 v[30:33], v0, s[4:5]
	s_cmpk_lt_i32 s3, 0x4000
	s_movk_i32 s7, 0x1fff
	s_cselect_b32 s7, 0xfff, s7
	s_and_b32 s6, s7, s3
	s_cmp_eq_u32 s6, 0
	s_cselect_b32 vcc_lo, 0, 0x400
	s_cmp_eq_u32 s6, s7
	s_cselect_b32 vcc_hi, 0, 0x400
	s_sub_u32 s6, s4, 0x2000000
	s_subb_u32 s7, s5, 0
	global_load_dwordx4 v[26:29], v0, s[6:7]
	s_sub_u32 s6, s4, vcc_lo
	s_subb_u32 s7, s5, 0
	global_load_dwordx4 v[34:37], v0, s[6:7]
	s_add_u32 s6, s4, vcc_hi
	s_addc_u32 s7, s5, 0
	global_load_dwordx4 v[38:41], v0, s[6:7]
.Lcv_loop:
	s_add_i32 s100, s3, s96
	s_cmpk_gt_i32 s100, 0x7fff
	s_cbranch_scc1 .Lcv_a_nois
	s_lshl_b32 s6, s100, 10
	s_add_u32 s4, s98, s6
	s_addc_u32 s5, s99, 0
	global_load_dwordx4 v[60:63], v0, s[4:5]
	s_cmpk_lt_i32 s100, 0x4000
	s_movk_i32 s7, 0x1fff
	s_cselect_b32 s7, 0xfff, s7
	s_and_b32 s6, s7, s100
	s_cmp_eq_u32 s6, 0
	s_cselect_b32 vcc_lo, 0, 0x400
	s_cmp_eq_u32 s6, s7
	s_cselect_b32 vcc_hi, 0, 0x400
	s_sub_u32 s6, s4, 0x2000000
	s_subb_u32 s7, s5, 0
	global_load_dwordx4 v[56:59], v0, s[6:7]
	s_sub_u32 s6, s4, vcc_lo
	s_subb_u32 s7, s5, 0
	global_load_dwordx4 v[64:67], v0, s[6:7]
	s_add_u32 s6, s4, vcc_hi
	s_addc_u32 s7, s5, 0
	global_load_dwordx4 v[68:71], v0, s[6:7]
	s_waitcnt vmcnt(4)
	s_branch .Lcv_a_go

; __device__ __forceinline__ u32x4 pack8(f32x4 a, f32x4 b) { u32x4 w; w.x = pk2(a[0], a[1]); w.y = pk2(a[2], a[3]); w.z = pk2(b[0], b[1]); w.w = pk2(b[2], b[3]); return w; }
; __device__ __forceinline__ void unpack8(u32x4 w, f32x4& a, f32x4& b) { a = (f32x4){bflo(w.x), bfhi(w.x), bflo(w.y), bfhi(w.y)}; b = (f32x4){bflo(w.z), bfhi(w.z), bflo(w.w), bfhi(w.w)}; }
; __global__ void __launch_bounds__(512, 2) mk_fwd(Args a) {
;     ...
;             for (int row = gw; row < T; row += NGW) {
;                 const int pos = tok_pos(row), S_ = row < TP ? 4096 : 8192;
;                 const u32x4 zc = *(const u32x4*)(CONVZ + (size_t)row * 512 + 8 * lane), bb = *(const u32x4*)(CONVB + (size_t)row * 512 + 8 * lane);
;                 u32x4 zp = (u32x4){0u, 0u, 0u, 0u}, zn = zp;
;                 if (pos > 0) zp = *(const u32x4*)(CONVZ + (size_t)(row - 1) * 512 + 8 * lane);
;                 if (pos < S_ - 1) zn = *(const u32x4*)(CONVZ + (size_t)(row + 1) * 512 + 8 * lane);
;                 f32x4 c0, c1, p0, p1, n0, n1, b0, b1; unpack8(zc, c0, c1); unpack8(zp, p0, p1); unpack8(zn, n0, n1); unpack8(bb, b0, b1);
;                 f32x4 y0, y1;
; #pragma unroll
;                 for (int e = 0; e < 4; ++e) { y0[e] = b0[e] * (w0[e] * p0[e] + w1[e] * c0[e] + w2[e] * n0[e]); y1[e] = b1[e] * (w0[4 + e] * p1[e] + w1[4 + e] * c1[e] + w2[4 + e] * n1[e]); }
;                 *(u32x4*)(CB + (size_t)row * 512 + 8 * lane) = pack8(y0, y1);
;             }
.Lcv_a_go:
	s_cmpk_lt_i32 s3, 0x4000
	s_movk_i32 s7, 0x1fff
	s_cselect_b32 s7, 0xfff, s7
	s_and_b32 s6, s7, s3
	s_cmp_lg_u32 s6, 0
	s_cbranch_scc1 .Lcv_a_p
	v_mov_b32_e32 v34, 0
	v_mov_b32_e32 v35, 0
	v_mov_b32_e32 v36, 0
	v_mov_b32_e32 v37, 0
.Lcv_a_p:
	s_cmp_lg_u32 s6, s7
	s_cbranch_scc1 .Lcv_a_n
	v_mov_b32_e32 v38, 0
	v_mov_b32_e32 v39, 0
	v_mov_b32_e32 v40, 0
	v_mov_b32_e32 v41, 0
.Lcv_a_n:
	v_lshlrev_b32_e32 v46, 16, v30
	v_and_b32_e32 v47, 0xffff0000, v30
	v_lshlrev_b32_e32 v30, 16, v31
	v_and_b32_e32 v31, 0xffff0000, v31
	v_lshlrev_b32_e32 v48, 16, v34
	v_and_b32_e32 v49, 0xffff0000, v34
	v_lshlrev_b32_e32 v34, 16, v35
	v_and_b32_e32 v35, 0xffff0000, v35
	v_pk_mul_f32 v[30:31], v[16:17], v[30:31]
	v_lshlrev_b32_e32 v50, 16, v38
	v_and_b32_e32 v51, 0xffff0000, v38
	v_lshlrev_b32_e32 v38, 16, v39
	v_and_b32_e32 v39, 0xffff0000, v39
	v_pk_fma_f32 v[30:31], v[8:9], v[34:35], v[30:31]
	v_lshlrev_b32_e32 v52, 16, v26
	v_and_b32_e32 v53, 0xffff0000, v26
	v_pk_mul_f32 v[46:47], v[14:15], v[46:47]
	v_lshlrev_b32_e32 v26, 16, v27
	v_and_b32_e32 v27, 0xffff0000, v27
	v_pk_fma_f32 v[30:31], v[20:21], v[38:39], v[30:31]
	v_pk_fma_f32 v[46:47], v[6:7], v[48:49], v[46:47]
	v_lshlrev_b32_e32 v48, 16, v32
	v_and_b32_e32 v49, 0xffff0000, v32
	v_pk_mul_f32 v[30:31], v[30:31], v[26:27]
	v_lshlrev_b32_e32 v26, 16, v33
	v_and_b32_e32 v27, 0xffff0000, v33
	v_pk_fma_f32 v[46:47], v[18:19], v[50:51], v[46:47]
	v_lshlrev_b32_e32 v50, 16, v36
	v_and_b32_e32 v51, 0xffff0000, v36
	v_pk_mul_f32 v[48:49], v[10:11], v[48:49]
	v_lshlrev_b32_e32 v32, 16, v37
	v_and_b32_e32 v33, 0xffff0000, v37
	v_pk_mul_f32 v[26:27], v[12:13], v[26:27]
	v_pk_mul_f32 v[46:47], v[46:47], v[52:53]
	v_lshlrev_b32_e32 v52, 16, v40
	v_and_b32_e32 v53, 0xffff0000, v40
	v_pk_fma_f32 v[48:49], v[2:3], v[50:51], v[48:49]
	v_lshlrev_b32_e32 v34, 16, v41
	v_and_b32_e32 v35, 0xffff0000, v41
	v_pk_fma_f32 v[26:27], v[4:5], v[32:33], v[26:27]
	v_lshlrev_b32_e32 v54, 16, v28
	v_and_b32_e32 v55, 0xffff0000, v28
	v_pk_fma_f32 v[48:49], v[22:23], v[52:53], v[48:49]
	v_lshlrev_b32_e32 v28, 16, v29
	v_and_b32_e32 v29, 0xffff0000, v29
	v_pk_fma_f32 v[26:27], v[24:25], v[34:35], v[26:27]
	v_pk_mul_f32 v[48:49], v[48:49], v[54:55]
	v_pk_mul_f32 v[32:33], v[26:27], v[28:29]
	v_cvt_pk_bf16_f32 v26, v46, v47
	v_cvt_pk_bf16_f32 v27, v30, v31
	v_cvt_pk_bf16_f32 v28, v48, v49
	v_cvt_pk_bf16_f32 v29, v32, v33
	s_lshl_b32 s6, s3, 10
	s_add_u32 s4, s98, s6
	s_addc_u32 s5, s99, 0
	s_add_u32 s4, s4, 0x5800000
	s_addc_u32 s5, s5, 0
	global_store_dwordx4 v0, v[26:29], s[4:5]
	s_cmpk_gt_i32 s100, 0x7fff
	s_cbranch_scc1 .LBB0_1558
	s_mov_b32 s3, s100
	s_add_i32 s100, s3, s96
	s_cmpk_gt_i32 s100, 0x7fff
	s_cbranch_scc1 .Lcv_b_nois
	s_lshl_b32 s6, s100, 10
	s_add_u32 s4, s98, s6
	s_addc_u32 s5, s99, 0
	global_load_dwordx4 v[30:33], v0, s[4:5]
	s_cmpk_lt_i32 s100, 0x4000
	s_movk_i32 s7, 0x1fff
	s_cselect_b32 s7, 0xfff, s7
	s_and_b32 s6, s7, s100
	s_cmp_eq_u32 s6, 0
	s_cselect_b32 vcc_lo, 0, 0x400
	s_cmp_eq_u32 s6, s7
	s_cselect_b32 vcc_hi, 0, 0x400
	s_sub_u32 s6, s4, 0x2000000
	s_subb_u32 s7, s5, 0
	global_load_dwordx4 v[26:29], v0, s[6:7]
	s_sub_u32 s6, s4, vcc_lo
	s_subb_u32 s7, s5, 0
	global_load_dwordx4 v[34:37], v0, s[6:7]
	s_add_u32 s6, s4, vcc_hi
	s_addc_u32 s7, s5, 0
	global_load_dwordx4 v[38:41], v0, s[6:7]
	s_waitcnt vmcnt(4)
	s_branch .Lcv_b_go

; __device__ __forceinline__ u32x4 pack8(f32x4 a, f32x4 b) { u32x4 w; w.x = pk2(a[0], a[1]); w.y = pk2(a[2], a[3]); w.z = pk2(b[0], b[1]); w.w = pk2(b[2], b[3]); return w; }
; __device__ __forceinline__ void unpack8(u32x4 w, f32x4& a, f32x4& b) { a = (f32x4){bflo(w.x), bfhi(w.x), bflo(w.y), bfhi(w.y)}; b = (f32x4){bflo(w.z), bfhi(w.z), bflo(w.w), bfhi(w.w)}; }
; __global__ void __launch_bounds__(512, 2) mk_fwd(Args a) {
;     ...
;             for (int row = gw; row < T; row += NGW) {
;                 const int pos = tok_pos(row), S_ = row < TP ? 4096 : 8192;
;                 const u32x4 zc = *(const u32x4*)(CONVZ + (size_t)row * 512 + 8 * lane), bb = *(const u32x4*)(CONVB + (size_t)row * 512 + 8 * lane);
;                 u32x4 zp = (u32x4){0u, 0u, 0u, 0u}, zn = zp;
;                 if (pos > 0) zp = *(const u32x4*)(CONVZ + (size_t)(row - 1) * 512 + 8 * lane);
;                 if (pos < S_ - 1) zn = *(const u32x4*)(CONVZ + (size_t)(row + 1) * 512 + 8 * lane);
;                 f32x4 c0, c1, p0, p1, n0, n1, b0, b1; unpack8(zc, c0, c1); unpack8(zp, p0, p1); unpack8(zn, n0, n1); unpack8(bb, b0, b1);
;                 f32x4 y0, y1;
; #pragma unroll
;                 for (int e = 0; e < 4; ++e) { y0[e] = b0[e] * (w0[e] * p0[e] + w1[e] * c0[e] + w2[e] * n0[e]); y1[e] = b1[e] * (w0[4 + e] * p1[e] + w1[4 + e] * c1[e] + w2[4 + e] * n1[e]); }
;                 *(u32x4*)(CB + (size_t)row * 512 + 8 * lane) = pack8(y0, y1);
;             }
.Lcv_b_go:
	s_cmpk_lt_i32 s3, 0x4000
	s_movk_i32 s7, 0x1fff
	s_cselect_b32 s7, 0xfff, s7
	s_and_b32 s6, s7, s3
	s_cmp_lg_u32 s6, 0
	s_cbranch_scc1 .Lcv_b_p
	v_mov_b32_e32 v64, 0
	v_mov_b32_e32 v65, 0
	v_mov_b32_e32 v66, 0
	v_mov_b32_e32 v67, 0
.Lcv_b_p:
	s_cmp_lg_u32 s6, s7
	s_cbranch_scc1 .Lcv_b_n
	v_mov_b32_e32 v68, 0
	v_mov_b32_e32 v69, 0
	v_mov_b32_e32 v70, 0
	v_mov_b32_e32 v71, 0
.Lcv_b_n:
	v_lshlrev_b32_e32 v72, 16, v60
	v_and_b32_e32 v73, 0xffff0000, v60
	v_lshlrev_b32_e32 v60, 16, v61
	v_and_b32_e32 v61, 0xffff0000, v61
	v_lshlrev_b32_e32 v74, 16, v64
	v_and_b32_e32 v75, 0xffff0000, v64
	v_lshlrev_b32_e32 v64, 16, v65
	v_and_b32_e32 v65, 0xffff0000, v65
	v_pk_mul_f32 v[60:61], v[16:17], v[60:61]
	v_lshlrev_b32_e32 v76, 16, v68
	v_and_b32_e32 v77, 0xffff0000, v68
	v_lshlrev_b32_e32 v68, 16, v69
	v_and_b32_e32 v69, 0xffff0000, v69
	v_pk_fma_f32 v[60:61], v[8:9], v[64:65], v[60:61]
	v_lshlrev_b32_e32 v78, 16, v56
	v_and_b32_e32 v79, 0xffff0000, v56
	v_pk_mul_f32 v[72:73], v[14:15], v[72:73]
	v_lshlrev_b32_e32 v56, 16, v57
	v_and_b32_e32 v57, 0xffff0000, v57
	v_pk_fma_f32 v[60:61], v[20:21], v[68:69], v[60:61]
	v_pk_fma_f32 v[72:73], v[6:7], v[74:75], v[72:73]
	v_lshlrev_b32_e32 v74, 16, v62
	v_and_b32_e32 v75, 0xffff0000, v62
	v_pk_mul_f32 v[60:61], v[60:61], v[56:57]
	v_lshlrev_b32_e32 v56, 16, v63
	v_and_b32_e32 v57, 0xffff0000, v63
	v_pk_fma_f32 v[72:73], v[18:19], v[76:77], v[72:73]
	v_lshlrev_b32_e32 v76, 16, v66
	v_and_b32_e32 v77, 0xffff0000, v66
	v_pk_mul_f32 v[74:75], v[10:11], v[74:75]
	v_lshlrev_b32_e32 v62, 16, v67
	v_and_b32_e32 v63, 0xffff0000, v67
	v_pk_mul_f32 v[56:57], v[12:13], v[56:57]
	v_pk_mul_f32 v[72:73], v[72:73], v[78:79]
	v_lshlrev_b32_e32 v78, 16, v70
	v_and_b32_e32 v79, 0xffff0000, v70
	v_pk_fma_f32 v[74:75], v[2:3], v[76:77], v[74:75]
	v_lshlrev_b32_e32 v64, 16, v71
	v_and_b32_e32 v65, 0xffff0000, v71
	v_pk_fma_f32 v[56:57], v[4:5], v[62:63], v[56:57]
	v_lshlrev_b32_e32 v80, 16, v58
	v_and_b32_e32 v81, 0xffff0000, v58
	v_pk_fma_f32 v[74:75], v[22:23], v[78:79], v[74:75]
	v_lshlrev_b32_e32 v58, 16, v59
	v_and_b32_e32 v59, 0xffff0000, v59
	v_pk_fma_f32 v[56:57], v[24:25], v[64:65], v[56:57]
	v_pk_mul_f32 v[74:75], v[74:75], v[80:81]
	v_pk_mul_f32 v[62:63], v[56:57], v[58:59]
	v_cvt_pk_bf16_f32 v56, v72, v73
	v_cvt_pk_bf16_f32 v57, v60, v61
	v_cvt_pk_bf16_f32 v58, v74, v75
	v_cvt_pk_bf16_f32 v59, v62, v63
	s_lshl_b32 s6, s3, 10
	s_add_u32 s4, s98, s6
	s_addc_u32 s5, s99, 0
	s_add_u32 s4, s4, 0x5800000
	s_addc_u32 s5, s5, 0
	global_store_dwordx4 v0, v[56:59], s[4:5]
	s_cmpk_gt_i32 s100, 0x7fff
	s_cbranch_scc1 .LBB0_1558
	s_mov_b32 s3, s100
	s_branch .Lcv_loop
